# sample-MLA tail O_lat.W_uv: unrolled, W_uv fragments prefetched 4 k-steps ahead, A double-buffered (on top of the priority + score-ring changes)
# baseline (speedup 1.0000x reference)
.LBB0_1177:
	v_lshl_add_u64 v[58:59], v[54:55], 0, s[50:51]
	v_add_co_u32_e32 v56, vcc, 0x3d00000, v58
	v_add_u32_e32 v76, s50, v52
	s_nop 0
	v_addc_co_u32_e32 v57, vcc, 0, v59, vcc
	v_add_co_u32_e32 v58, vcc, 0x3d08000, v58
	s_nop 1
	v_addc_co_u32_e32 v59, vcc, 0, v59, vcc
	global_load_dwordx4 v[134:137], v[56:57], off offset:128
	global_load_dwordx4 v[138:141], v[58:59], off offset:128
	global_load_dwordx4 v[142:145], v[56:57], off offset:160
	global_load_dwordx4 v[146:149], v[58:59], off offset:160
	global_load_dwordx4 v[150:153], v[56:57], off offset:192
	global_load_dwordx4 v[154:157], v[58:59], off offset:192
	global_load_dwordx4 v[158:161], v[56:57], off offset:224
	global_load_dwordx4 v[162:165], v[58:59], off offset:224
	v_add_u32_e32 v1, 0x80, v76
	v_xad_u32 v1, v1, v51, v75
	ds_read_b128 v[78:81], v1
	v_add_u32_e32 v1, 0xa0, v76
	v_xad_u32 v1, v1, v51, v75
	ds_read_b128 v[82:85], v1
	s_waitcnt vmcnt(6) lgkmcnt(1)
	v_mfma_f32_32x32x16_bf16 v[20:35], v[78:81], v[134:137], v[20:35]
	v_mfma_f32_32x32x16_bf16 v[4:19], v[78:81], v[138:141], v[4:19]
	v_add_u32_e32 v1, 0xc0, v76
	v_xad_u32 v1, v1, v51, v75
	ds_read_b128 v[78:81], v1
	global_load_dwordx4 v[134:137], v[56:57], off offset:256
	global_load_dwordx4 v[138:141], v[58:59], off offset:256
	s_waitcnt vmcnt(6) lgkmcnt(1)
	v_mfma_f32_32x32x16_bf16 v[20:35], v[82:85], v[142:145], v[20:35]
	v_mfma_f32_32x32x16_bf16 v[4:19], v[82:85], v[146:149], v[4:19]
	v_add_u32_e32 v1, 0xe0, v76
	v_xad_u32 v1, v1, v51, v75
	ds_read_b128 v[82:85], v1
	global_load_dwordx4 v[142:145], v[56:57], off offset:288
	global_load_dwordx4 v[146:149], v[58:59], off offset:288
	s_waitcnt vmcnt(6) lgkmcnt(1)
	v_mfma_f32_32x32x16_bf16 v[20:35], v[78:81], v[150:153], v[20:35]
	v_mfma_f32_32x32x16_bf16 v[4:19], v[78:81], v[154:157], v[4:19]
	v_add_u32_e32 v1, 0x100, v76
	v_xad_u32 v1, v1, v51, v75
	ds_read_b128 v[78:81], v1
	global_load_dwordx4 v[150:153], v[56:57], off offset:320
	global_load_dwordx4 v[154:157], v[58:59], off offset:320
	s_waitcnt vmcnt(6) lgkmcnt(1)
	v_mfma_f32_32x32x16_bf16 v[20:35], v[82:85], v[158:161], v[20:35]
	v_mfma_f32_32x32x16_bf16 v[4:19], v[82:85], v[162:165], v[4:19]
	v_add_u32_e32 v1, 0x120, v76
	v_xad_u32 v1, v1, v51, v75
	ds_read_b128 v[82:85], v1
	global_load_dwordx4 v[158:161], v[56:57], off offset:352
	global_load_dwordx4 v[162:165], v[58:59], off offset:352
	s_waitcnt vmcnt(6) lgkmcnt(1)
	v_mfma_f32_32x32x16_bf16 v[20:35], v[78:81], v[134:137], v[20:35]
	v_mfma_f32_32x32x16_bf16 v[4:19], v[78:81], v[138:141], v[4:19]
	v_add_u32_e32 v1, 0x140, v76
	v_xad_u32 v1, v1, v51, v75
	ds_read_b128 v[78:81], v1
	global_load_dwordx4 v[134:137], v[56:57], off offset:384
	global_load_dwordx4 v[138:141], v[58:59], off offset:384
	s_waitcnt vmcnt(6) lgkmcnt(1)
	v_mfma_f32_32x32x16_bf16 v[20:35], v[82:85], v[142:145], v[20:35]
	v_mfma_f32_32x32x16_bf16 v[4:19], v[82:85], v[146:149], v[4:19]
	v_add_u32_e32 v1, 0x160, v76
	v_xad_u32 v1, v1, v51, v75
	ds_read_b128 v[82:85], v1
	global_load_dwordx4 v[142:145], v[56:57], off offset:416
	global_load_dwordx4 v[146:149], v[58:59], off offset:416
	s_waitcnt vmcnt(6) lgkmcnt(1)
	v_mfma_f32_32x32x16_bf16 v[20:35], v[78:81], v[150:153], v[20:35]
	v_mfma_f32_32x32x16_bf16 v[4:19], v[78:81], v[154:157], v[4:19]
	v_add_u32_e32 v1, 0x180, v76
	v_xad_u32 v1, v1, v51, v75
	ds_read_b128 v[78:81], v1
	global_load_dwordx4 v[150:153], v[56:57], off offset:448
	global_load_dwordx4 v[154:157], v[58:59], off offset:448
	s_waitcnt vmcnt(6) lgkmcnt(1)
	v_mfma_f32_32x32x16_bf16 v[20:35], v[82:85], v[158:161], v[20:35]
	v_mfma_f32_32x32x16_bf16 v[4:19], v[82:85], v[162:165], v[4:19]
	v_add_u32_e32 v1, 0x1a0, v76
	v_xad_u32 v1, v1, v51, v75
	ds_read_b128 v[82:85], v1
	global_load_dwordx4 v[158:161], v[56:57], off offset:480
	global_load_dwordx4 v[162:165], v[58:59], off offset:480
	s_waitcnt vmcnt(6) lgkmcnt(1)
	v_mfma_f32_32x32x16_bf16 v[20:35], v[78:81], v[134:137], v[20:35]
	v_mfma_f32_32x32x16_bf16 v[4:19], v[78:81], v[138:141], v[4:19]
	v_add_u32_e32 v1, 0x1c0, v76
	v_xad_u32 v1, v1, v51, v75
	ds_read_b128 v[78:81], v1
	global_load_dwordx4 v[134:137], v[56:57], off offset:512
	global_load_dwordx4 v[138:141], v[58:59], off offset:512
	s_waitcnt vmcnt(6) lgkmcnt(1)
	v_mfma_f32_32x32x16_bf16 v[20:35], v[82:85], v[142:145], v[20:35]
	v_mfma_f32_32x32x16_bf16 v[4:19], v[82:85], v[146:149], v[4:19]
	v_add_u32_e32 v1, 0x1e0, v76
	v_xad_u32 v1, v1, v51, v75
	ds_read_b128 v[82:85], v1
	global_load_dwordx4 v[142:145], v[56:57], off offset:544
	global_load_dwordx4 v[146:149], v[58:59], off offset:544
	s_waitcnt vmcnt(6) lgkmcnt(1)
	v_mfma_f32_32x32x16_bf16 v[20:35], v[78:81], v[150:153], v[20:35]
	v_mfma_f32_32x32x16_bf16 v[4:19], v[78:81], v[154:157], v[4:19]
	v_add_u32_e32 v1, 0x200, v76
	v_xad_u32 v1, v1, v51, v75
	ds_read_b128 v[78:81], v1
	global_load_dwordx4 v[150:153], v[56:57], off offset:576
	global_load_dwordx4 v[154:157], v[58:59], off offset:576
	s_waitcnt vmcnt(6) lgkmcnt(1)
	v_mfma_f32_32x32x16_bf16 v[20:35], v[82:85], v[158:161], v[20:35]
	v_mfma_f32_32x32x16_bf16 v[4:19], v[82:85], v[162:165], v[4:19]
	v_add_u32_e32 v1, 0x220, v76
	v_xad_u32 v1, v1, v51, v75
	ds_read_b128 v[82:85], v1
	global_load_dwordx4 v[158:161], v[56:57], off offset:608
	global_load_dwordx4 v[162:165], v[58:59], off offset:608
	s_waitcnt vmcnt(6) lgkmcnt(1)
	v_mfma_f32_32x32x16_bf16 v[20:35], v[78:81], v[134:137], v[20:35]
	v_mfma_f32_32x32x16_bf16 v[4:19], v[78:81], v[138:141], v[4:19]
	v_add_u32_e32 v1, 0x240, v76
	v_xad_u32 v1, v1, v51, v75
	ds_read_b128 v[78:81], v1
	global_load_dwordx4 v[134:137], v[56:57], off offset:640
	global_load_dwordx4 v[138:141], v[58:59], off offset:640
	s_waitcnt vmcnt(6) lgkmcnt(1)
	v_mfma_f32_32x32x16_bf16 v[20:35], v[82:85], v[142:145], v[20:35]
	v_mfma_f32_32x32x16_bf16 v[4:19], v[82:85], v[146:149], v[4:19]
	v_add_u32_e32 v1, 0x260, v76
	v_xad_u32 v1, v1, v51, v75
	ds_read_b128 v[82:85], v1
	global_load_dwordx4 v[142:145], v[56:57], off offset:672
	global_load_dwordx4 v[146:149], v[58:59], off offset:672
	s_waitcnt vmcnt(6) lgkmcnt(1)
	v_mfma_f32_32x32x16_bf16 v[20:35], v[78:81], v[150:153], v[20:35]
	v_mfma_f32_32x32x16_bf16 v[4:19], v[78:81], v[154:157], v[4:19]
	v_add_u32_e32 v1, 0x280, v76
	v_xad_u32 v1, v1, v51, v75
	ds_read_b128 v[78:81], v1
	global_load_dwordx4 v[150:153], v[56:57], off offset:704
	global_load_dwordx4 v[154:157], v[58:59], off offset:704
	s_waitcnt vmcnt(6) lgkmcnt(1)
	v_mfma_f32_32x32x16_bf16 v[20:35], v[82:85], v[158:161], v[20:35]
	v_mfma_f32_32x32x16_bf16 v[4:19], v[82:85], v[162:165], v[4:19]
	v_add_u32_e32 v1, 0x2a0, v76
	v_xad_u32 v1, v1, v51, v75
	ds_read_b128 v[82:85], v1
	global_load_dwordx4 v[158:161], v[56:57], off offset:736
	global_load_dwordx4 v[162:165], v[58:59], off offset:736
	s_waitcnt vmcnt(6) lgkmcnt(1)
	v_mfma_f32_32x32x16_bf16 v[20:35], v[78:81], v[134:137], v[20:35]
	v_mfma_f32_32x32x16_bf16 v[4:19], v[78:81], v[138:141], v[4:19]
	v_add_u32_e32 v1, 0x2c0, v76
	v_xad_u32 v1, v1, v51, v75
	ds_read_b128 v[78:81], v1
	global_load_dwordx4 v[134:137], v[56:57], off offset:768
	global_load_dwordx4 v[138:141], v[58:59], off offset:768
	s_waitcnt vmcnt(6) lgkmcnt(1)
	v_mfma_f32_32x32x16_bf16 v[20:35], v[82:85], v[142:145], v[20:35]
	v_mfma_f32_32x32x16_bf16 v[4:19], v[82:85], v[146:149], v[4:19]
	v_add_u32_e32 v1, 0x2e0, v76
	v_xad_u32 v1, v1, v51, v75
	ds_read_b128 v[82:85], v1
	global_load_dwordx4 v[142:145], v[56:57], off offset:800
	global_load_dwordx4 v[146:149], v[58:59], off offset:800
	s_waitcnt vmcnt(6) lgkmcnt(1)
	v_mfma_f32_32x32x16_bf16 v[20:35], v[78:81], v[150:153], v[20:35]
	v_mfma_f32_32x32x16_bf16 v[4:19], v[78:81], v[154:157], v[4:19]
	v_add_u32_e32 v1, 0x300, v76
	v_xad_u32 v1, v1, v51, v75
	ds_read_b128 v[78:81], v1
	global_load_dwordx4 v[150:153], v[56:57], off offset:832
	global_load_dwordx4 v[154:157], v[58:59], off offset:832
	s_waitcnt vmcnt(6) lgkmcnt(1)
	v_mfma_f32_32x32x16_bf16 v[20:35], v[82:85], v[158:161], v[20:35]
	v_mfma_f32_32x32x16_bf16 v[4:19], v[82:85], v[162:165], v[4:19]
	v_add_u32_e32 v1, 0x320, v76
	v_xad_u32 v1, v1, v51, v75
	ds_read_b128 v[82:85], v1
	global_load_dwordx4 v[158:161], v[56:57], off offset:864
	global_load_dwordx4 v[162:165], v[58:59], off offset:864
	s_waitcnt vmcnt(6) lgkmcnt(1)
	v_mfma_f32_32x32x16_bf16 v[20:35], v[78:81], v[134:137], v[20:35]
	v_mfma_f32_32x32x16_bf16 v[4:19], v[78:81], v[138:141], v[4:19]
	v_add_u32_e32 v1, 0x340, v76
	v_xad_u32 v1, v1, v51, v75
	ds_read_b128 v[78:81], v1
	global_load_dwordx4 v[134:137], v[56:57], off offset:896
	global_load_dwordx4 v[138:141], v[58:59], off offset:896
	s_waitcnt vmcnt(6) lgkmcnt(1)
	v_mfma_f32_32x32x16_bf16 v[20:35], v[82:85], v[142:145], v[20:35]
	v_mfma_f32_32x32x16_bf16 v[4:19], v[82:85], v[146:149], v[4:19]
	v_add_u32_e32 v1, 0x360, v76
	v_xad_u32 v1, v1, v51, v75
	ds_read_b128 v[82:85], v1
	global_load_dwordx4 v[142:145], v[56:57], off offset:928
	global_load_dwordx4 v[146:149], v[58:59], off offset:928
	s_waitcnt vmcnt(6) lgkmcnt(1)
	v_mfma_f32_32x32x16_bf16 v[20:35], v[78:81], v[150:153], v[20:35]
	v_mfma_f32_32x32x16_bf16 v[4:19], v[78:81], v[154:157], v[4:19]
	v_add_u32_e32 v1, 0x380, v76
	v_xad_u32 v1, v1, v51, v75
	ds_read_b128 v[78:81], v1
	global_load_dwordx4 v[150:153], v[56:57], off offset:960
	global_load_dwordx4 v[154:157], v[58:59], off offset:960
	s_waitcnt vmcnt(6) lgkmcnt(1)
	v_mfma_f32_32x32x16_bf16 v[20:35], v[82:85], v[158:161], v[20:35]
	v_mfma_f32_32x32x16_bf16 v[4:19], v[82:85], v[162:165], v[4:19]
	v_add_u32_e32 v1, 0x3a0, v76
	v_xad_u32 v1, v1, v51, v75
	ds_read_b128 v[82:85], v1
	global_load_dwordx4 v[158:161], v[56:57], off offset:992
	global_load_dwordx4 v[162:165], v[58:59], off offset:992
	s_waitcnt vmcnt(6) lgkmcnt(1)
	v_mfma_f32_32x32x16_bf16 v[20:35], v[78:81], v[134:137], v[20:35]
	v_mfma_f32_32x32x16_bf16 v[4:19], v[78:81], v[138:141], v[4:19]
	v_add_u32_e32 v1, 0x3c0, v76
	v_xad_u32 v1, v1, v51, v75
	ds_read_b128 v[78:81], v1
	s_waitcnt vmcnt(4) lgkmcnt(1)
	v_mfma_f32_32x32x16_bf16 v[20:35], v[82:85], v[142:145], v[20:35]
	v_mfma_f32_32x32x16_bf16 v[4:19], v[82:85], v[146:149], v[4:19]
	v_add_u32_e32 v1, 0x3e0, v76
	v_xad_u32 v1, v1, v51, v75
	ds_read_b128 v[82:85], v1
	s_waitcnt vmcnt(2) lgkmcnt(1)
	v_mfma_f32_32x32x16_bf16 v[20:35], v[78:81], v[150:153], v[20:35]
	v_mfma_f32_32x32x16_bf16 v[4:19], v[78:81], v[154:157], v[4:19]
	s_waitcnt vmcnt(0) lgkmcnt(0)
	v_mfma_f32_32x32x16_bf16 v[20:35], v[82:85], v[158:161], v[20:35]
	v_mfma_f32_32x32x16_bf16 v[4:19], v[82:85], v[162:165], v[4:19]
	s_nop 3
	s_nop 8
	v_cndmask_b32_e64 v1, v20, v21, s[44:45]
	s_lshl_b64 s[12:13], s[46:47], 1
	v_readlane_b32 s9, v254, 31
	ds_bpermute_b32 v1, v212, v1
	s_add_u32 s9, s9, s12
	v_readlane_b32 s12, v254, 32
	s_addc_u32 s12, s12, s13
	s_add_u32 s9, s9, s48
	s_addc_u32 s13, s12, s49
	s_add_u32 s12, s9, s1
	s_waitcnt lgkmcnt(0)
	v_cndmask_b32_e64 v20, v1, v20, s[44:45]
	v_cndmask_b32_e64 v1, v21, v1, s[44:45]
	v_lshlrev_b32_e32 v21, 16, v74
	s_addc_u32 s13, s13, 0
	v_lshlrev_b32_e32 v50, 1, v50
	v_mov_b32_e32 v51, v3
	v_mul_f32_e32 v20, v20, v21
	v_and_b32_e32 v21, 0xffff0000, v74
	v_lshl_add_u64 v[50:51], s[12:13], 0, v[50:51]
	v_mul_f32_e32 v1, v1, v21
	v_cvt_pk_bf16_f32 v1, v20, v1
	v_lshl_add_u64 v[20:21], v[50:51], 0, v[2:3]
	global_store_dword v[20:21], v1, off
	v_cndmask_b32_e64 v1, v22, v23, s[44:45]
	ds_bpermute_b32 v1, v212, v1
	s_waitcnt lgkmcnt(0)
	v_cndmask_b32_e64 v2, v1, v22, s[44:45]
	v_lshlrev_b32_e32 v22, 16, v73
	v_cndmask_b32_e64 v1, v23, v1, s[44:45]
	v_mul_f32_e32 v2, v2, v22
	v_and_b32_e32 v22, 0xffff0000, v73
	v_mul_f32_e32 v1, v1, v22
	v_cvt_pk_bf16_f32 v1, v2, v1
	v_lshl_add_u64 v[22:23], v[50:51], 0, v[48:49]
	global_store_dword v[22:23], v1, off
	v_cndmask_b32_e64 v1, v24, v25, s[44:45]
	ds_bpermute_b32 v1, v212, v1
	v_lshlrev_b32_e32 v22, 16, v72
	s_waitcnt lgkmcnt(0)
	v_cndmask_b32_e64 v2, v1, v24, s[44:45]
	v_cndmask_b32_e64 v1, v25, v1, s[44:45]
	v_mul_f32_e32 v2, v2, v22
	v_and_b32_e32 v22, 0xffff0000, v72
	v_mul_f32_e32 v1, v1, v22
	v_cvt_pk_bf16_f32 v1, v2, v1
	v_lshl_add_u64 v[22:23], v[50:51], 0, v[46:47]
	global_store_dword v[22:23], v1, off
	v_cndmask_b32_e64 v1, v26, v27, s[44:45]
	ds_bpermute_b32 v1, v212, v1
	v_lshlrev_b32_e32 v22, 16, v71
	s_waitcnt lgkmcnt(0)
	v_cndmask_b32_e64 v2, v1, v26, s[44:45]
	v_cndmask_b32_e64 v1, v27, v1, s[44:45]
	v_mul_f32_e32 v2, v2, v22
	v_and_b32_e32 v22, 0xffff0000, v71
	v_mul_f32_e32 v1, v1, v22
	v_cvt_pk_bf16_f32 v1, v2, v1
	v_lshl_add_u64 v[22:23], v[50:51], 0, v[44:45]
	global_store_dword v[22:23], v1, off
	v_cndmask_b32_e64 v1, v28, v29, s[44:45]
	ds_bpermute_b32 v1, v212, v1
	v_lshlrev_b32_e32 v22, 16, v70
	s_waitcnt lgkmcnt(0)
	v_cndmask_b32_e64 v2, v1, v28, s[44:45]
	v_cndmask_b32_e64 v1, v29, v1, s[44:45]
	v_mul_f32_e32 v2, v2, v22
	v_and_b32_e32 v22, 0xffff0000, v70
	v_mul_f32_e32 v1, v1, v22
	v_cvt_pk_bf16_f32 v1, v2, v1
	v_lshl_add_u64 v[22:23], v[50:51], 0, v[42:43]
	global_store_dword v[22:23], v1, off
	v_cndmask_b32_e64 v1, v30, v31, s[44:45]
	ds_bpermute_b32 v1, v212, v1
	v_lshlrev_b32_e32 v22, 16, v69
	s_waitcnt lgkmcnt(0)
	v_cndmask_b32_e64 v2, v1, v30, s[44:45]
	v_cndmask_b32_e64 v1, v31, v1, s[44:45]
	v_mul_f32_e32 v2, v2, v22
	v_and_b32_e32 v22, 0xffff0000, v69
	v_mul_f32_e32 v1, v1, v22
	v_cvt_pk_bf16_f32 v1, v2, v1
	v_lshl_add_u64 v[22:23], v[50:51], 0, v[40:41]
	global_store_dword v[22:23], v1, off
	v_cndmask_b32_e64 v1, v32, v33, s[44:45]
	ds_bpermute_b32 v1, v212, v1
	v_lshlrev_b32_e32 v22, 16, v68
	s_waitcnt lgkmcnt(0)
	v_cndmask_b32_e64 v2, v1, v32, s[44:45]
	v_cndmask_b32_e64 v1, v33, v1, s[44:45]
	v_mul_f32_e32 v2, v2, v22
	v_and_b32_e32 v22, 0xffff0000, v68
	v_mul_f32_e32 v1, v1, v22
	v_cvt_pk_bf16_f32 v1, v2, v1
	v_lshl_add_u64 v[22:23], v[50:51], 0, v[38:39]
	global_store_dword v[22:23], v1, off
	v_cndmask_b32_e64 v1, v34, v35, s[44:45]
	ds_bpermute_b32 v1, v212, v1
	v_lshlrev_b32_e32 v22, 16, v67
	s_waitcnt lgkmcnt(0)
	v_cndmask_b32_e64 v2, v1, v34, s[44:45]
	v_cndmask_b32_e64 v1, v35, v1, s[44:45]
	v_mul_f32_e32 v2, v2, v22
	v_and_b32_e32 v22, 0xffff0000, v67
	v_mul_f32_e32 v1, v1, v22
	v_cvt_pk_bf16_f32 v1, v2, v1
	v_lshl_add_u64 v[22:23], v[50:51], 0, v[36:37]
	global_store_dword v[22:23], v1, off
	v_cndmask_b32_e64 v1, v4, v5, s[44:45]
	ds_bpermute_b32 v1, v212, v1
	v_lshl_add_u64 v[22:23], v[50:51], 0, 64
	s_waitcnt lgkmcnt(0)
	v_cndmask_b32_e64 v2, v1, v4, s[44:45]
	v_lshlrev_b32_e32 v4, 16, v66
	v_cndmask_b32_e64 v1, v5, v1, s[44:45]
	v_mul_f32_e32 v2, v2, v4
	v_and_b32_e32 v4, 0xffff0000, v66
	v_mul_f32_e32 v1, v1, v4
	v_cvt_pk_bf16_f32 v1, v2, v1
	global_store_dword v[20:21], v1, off offset:64
	v_cndmask_b32_e64 v1, v6, v7, s[44:45]
	ds_bpermute_b32 v1, v212, v1
	v_lshlrev_b32_e32 v4, 16, v65
	s_waitcnt lgkmcnt(0)
	v_cndmask_b32_e64 v2, v1, v6, s[44:45]
	v_cndmask_b32_e64 v1, v7, v1, s[44:45]
	v_mul_f32_e32 v2, v2, v4
	v_and_b32_e32 v4, 0xffff0000, v65
	v_mul_f32_e32 v1, v1, v4
	v_cvt_pk_bf16_f32 v1, v2, v1
	v_lshl_add_u64 v[4:5], v[22:23], 0, v[48:49]
	global_store_dword v[4:5], v1, off
	v_cndmask_b32_e64 v1, v8, v9, s[44:45]
	ds_bpermute_b32 v1, v212, v1
	v_lshlrev_b32_e32 v4, 16, v64
	s_waitcnt lgkmcnt(0)
	v_cndmask_b32_e64 v2, v1, v8, s[44:45]
	v_cndmask_b32_e64 v1, v9, v1, s[44:45]
	v_mul_f32_e32 v2, v2, v4
	v_and_b32_e32 v4, 0xffff0000, v64
	v_mul_f32_e32 v1, v1, v4
	v_cvt_pk_bf16_f32 v1, v2, v1
	v_lshl_add_u64 v[4:5], v[22:23], 0, v[46:47]
	global_store_dword v[4:5], v1, off
	v_cndmask_b32_e64 v1, v10, v11, s[44:45]
	ds_bpermute_b32 v1, v212, v1
	v_lshlrev_b32_e32 v4, 16, v63
	s_waitcnt lgkmcnt(0)
	v_cndmask_b32_e64 v2, v1, v10, s[44:45]
	v_cndmask_b32_e64 v1, v11, v1, s[44:45]
	v_mul_f32_e32 v2, v2, v4
	v_and_b32_e32 v4, 0xffff0000, v63
	v_mul_f32_e32 v1, v1, v4
	v_cvt_pk_bf16_f32 v1, v2, v1
	v_lshl_add_u64 v[4:5], v[22:23], 0, v[44:45]
	global_store_dword v[4:5], v1, off
	v_cndmask_b32_e64 v1, v12, v13, s[44:45]
	ds_bpermute_b32 v1, v212, v1
	v_lshlrev_b32_e32 v4, 16, v62
	s_waitcnt lgkmcnt(0)
	v_cndmask_b32_e64 v2, v1, v12, s[44:45]
	v_cndmask_b32_e64 v1, v13, v1, s[44:45]
	v_mul_f32_e32 v2, v2, v4
	v_and_b32_e32 v4, 0xffff0000, v62
	v_mul_f32_e32 v1, v1, v4
	v_cvt_pk_bf16_f32 v1, v2, v1
	v_lshl_add_u64 v[4:5], v[22:23], 0, v[42:43]
	global_store_dword v[4:5], v1, off
	v_cndmask_b32_e64 v1, v14, v15, s[44:45]
	ds_bpermute_b32 v1, v212, v1
	v_lshlrev_b32_e32 v4, 16, v61
	s_waitcnt lgkmcnt(0)
	v_cndmask_b32_e64 v2, v1, v14, s[44:45]
	v_cndmask_b32_e64 v1, v15, v1, s[44:45]
	v_mul_f32_e32 v2, v2, v4
	v_and_b32_e32 v4, 0xffff0000, v61
	v_mul_f32_e32 v1, v1, v4
	v_cvt_pk_bf16_f32 v1, v2, v1
	v_lshl_add_u64 v[4:5], v[22:23], 0, v[40:41]
	global_store_dword v[4:5], v1, off
	v_cndmask_b32_e64 v1, v16, v17, s[44:45]
	ds_bpermute_b32 v1, v212, v1
	v_lshlrev_b32_e32 v4, 16, v60
	s_waitcnt lgkmcnt(0)
	v_cndmask_b32_e64 v2, v1, v16, s[44:45]
	v_cndmask_b32_e64 v1, v17, v1, s[44:45]
	v_mul_f32_e32 v2, v2, v4
	v_and_b32_e32 v4, 0xffff0000, v60
	v_mul_f32_e32 v1, v1, v4
	v_cvt_pk_bf16_f32 v1, v2, v1
	v_lshl_add_u64 v[4:5], v[22:23], 0, v[38:39]
	global_store_dword v[4:5], v1, off
	v_cndmask_b32_e64 v1, v18, v19, s[44:45]
	ds_bpermute_b32 v1, v212, v1
	v_lshlrev_b32_e32 v4, 16, v53
	s_waitcnt lgkmcnt(0)
	v_cndmask_b32_e64 v2, v1, v18, s[44:45]
	v_cndmask_b32_e64 v1, v19, v1, s[44:45]
	v_mul_f32_e32 v2, v2, v4
	v_and_b32_e32 v4, 0xffff0000, v53
	v_mul_f32_e32 v1, v1, v4
	v_cvt_pk_bf16_f32 v1, v2, v1
	v_lshl_add_u64 v[4:5], v[22:23], 0, v[36:37]
	global_store_dword v[4:5], v1, off
	s_barrier
	s_branch .LBB0_874
	s_nop 0
